# lever 1 (wait placement): chunk-prep next-task input selects moved from right after the loads to the start of S4, so the prefetch really overlaps S2/S3
# speedup vs baseline: 1.0079x; 1.0079x over previous
.LBB0_370:
	s_or_b64 exec, exec, s[6:7]
	s_lshl_b32 s6, s24, 6
	s_ashr_i32 s5, s4, 31
	s_and_b32 s25, s6, 0x7c0
	s_lshl_b64 s[4:5], s[4:5], 18
	s_lshl_b32 s6, s25, 7
	s_or_b32 s4, s4, s6
	s_add_i32 s65, s24, s88
	s_cmpk_gt_i32 s65, 0x7ff
	s_cselect_b64 s[26:27], -1, 0
	s_cmpk_lt_i32 s65, 0x800
	v_and_b32_e32 v142, 15, v132
	v_ashrrev_i32_e32 v128, 4, v132
	s_cselect_b32 s31, s65, -1
	s_add_i32 s7, 0, 0x1f700
	v_lshlrev_b32_e32 v112, 2, v128
	v_lshl_add_u32 v97, v142, 5, 0
	s_waitcnt lgkmcnt(0)
	s_barrier
	v_add_u32_e32 v105, s7, v112
	v_add_u32_e32 v124, 0x20400, v97
	ds_read_b32 v96, v105
	ds_read_b128 v[100:103], v124 offset:1552
	ds_read_b128 v[108:111], v124 offset:16
	ds_read_b128 v[114:117], v124 offset:528
	ds_read_b128 v[118:121], v124 offset:1040
	v_lshlrev_b32_e32 v136, 16, v43
	v_and_b32_e32 v137, 0xffff0000, v43
	v_lshlrev_b32_e32 v126, 16, v51
	v_and_b32_e32 v127, 0xffff0000, v51
	s_waitcnt lgkmcnt(2)
	v_pk_fma_f32 v[136:137], v[110:111], v[136:137], 0 op_sel_hi:[1,1,0]
	v_lshlrev_b32_e32 v138, 16, v50
	v_and_b32_e32 v139, 0xffff0000, v50
	v_lshlrev_b32_e32 v122, 16, v63
	v_and_b32_e32 v123, 0xffff0000, v63
	v_pk_fma_f32 v[138:139], v[108:109], v[138:139], 0 op_sel_hi:[1,1,0]
	v_lshlrev_b32_e32 v146, 16, v3
	v_and_b32_e32 v147, 0xffff0000, v3
	s_waitcnt lgkmcnt(1)
	v_pk_fma_f32 v[126:127], v[116:117], v[126:127], v[136:137]
	v_lshlrev_b32_e32 v136, 16, v56
	v_and_b32_e32 v137, 0xffff0000, v56
	v_pk_fma_f32 v[146:147], v[110:111], v[146:147], 0 op_sel_hi:[1,1,0]
	v_lshlrev_b32_e32 v110, 16, v2
	v_and_b32_e32 v111, 0xffff0000, v2
	v_pk_fma_f32 v[136:137], v[114:115], v[136:137], v[138:139]
	v_lshlrev_b32_e32 v138, 16, v7
	v_and_b32_e32 v139, 0xffff0000, v7
	s_waitcnt lgkmcnt(0)
	v_pk_fma_f32 v[122:123], v[120:121], v[122:123], v[126:127]
	v_lshlrev_b32_e32 v126, 16, v64
	v_and_b32_e32 v127, 0xffff0000, v64
	v_pk_fma_f32 v[148:149], v[108:109], v[110:111], 0 op_sel_hi:[1,1,0]
	v_pk_fma_f32 v[138:139], v[116:117], v[138:139], v[146:147]
	v_lshlrev_b32_e32 v116, 16, v6
	v_and_b32_e32 v117, 0xffff0000, v6
	v_pk_fma_f32 v[126:127], v[118:119], v[126:127], v[136:137]
	v_lshlrev_b32_e32 v136, 16, v11
	v_and_b32_e32 v137, 0xffff0000, v11
	v_mov_b32_e32 v107, s23
	v_mul_f32_e32 v96, 0x3fb8aa3b, v96
	v_pk_fma_f32 v[146:147], v[114:115], v[116:117], v[148:149]
	v_pk_fma_f32 v[136:137], v[120:121], v[136:137], v[138:139]
	v_lshlrev_b32_e32 v120, 16, v10
	v_and_b32_e32 v121, 0xffff0000, v10
	v_exp_f32_e32 v106, v96
	ds_read_b128 v[96:99], v124 offset:512
	ds_read_b128 v[108:111], v124 offset:1024
	ds_read_b128 v[114:117], v124 offset:1536
	v_pk_fma_f32 v[138:139], v[118:119], v[120:121], v[146:147]
	ds_read_b32 v141, v107
	ds_read_b128 v[118:121], v124
	s_waitcnt vmcnt(5)
	v_lshlrev_b32_e32 v146, 16, v19
	v_and_b32_e32 v147, 0xffff0000, v19
	v_lshlrev_b32_e32 v148, 16, v15
	v_and_b32_e32 v149, 0xffff0000, v15
	v_pk_fma_f32 v[122:123], v[102:103], v[146:147], v[122:123]
	v_lshlrev_b32_e32 v146, 16, v18
	v_and_b32_e32 v147, 0xffff0000, v18
	v_pk_fma_f32 v[102:103], v[102:103], v[148:149], v[136:137]
	v_lshlrev_b32_e32 v136, 16, v14
	v_and_b32_e32 v137, 0xffff0000, v14
	v_pk_fma_f32 v[126:127], v[100:101], v[146:147], v[126:127]
	v_pk_fma_f32 v[136:137], v[100:101], v[136:137], v[138:139]
	v_lshlrev_b32_e32 v100, 16, v40
	v_and_b32_e32 v101, 0xffff0000, v40
	v_lshlrev_b32_e32 v146, 16, v41
	v_and_b32_e32 v147, 0xffff0000, v41
	s_waitcnt lgkmcnt(0)
	v_pk_fma_f32 v[138:139], v[118:119], v[100:101], 0 op_sel_hi:[1,1,0]
	v_lshlrev_b32_e32 v100, 16, v1
	v_and_b32_e32 v101, 0xffff0000, v1
	v_pk_fma_f32 v[146:147], v[120:121], v[146:147], 0 op_sel_hi:[1,1,0]
	v_pk_fma_f32 v[120:121], v[120:121], v[100:101], 0 op_sel_hi:[1,1,0]
	v_lshlrev_b32_e32 v100, 16, v0
	v_and_b32_e32 v101, 0xffff0000, v0
	v_pk_fma_f32 v[118:119], v[118:119], v[100:101], 0 op_sel_hi:[1,1,0]
	v_mul_f32_e32 v100, 0xbfb8aa3b, v122
	v_exp_f32_e32 v100, v100
	v_mul_f32_e32 v101, 0xbfb8aa3b, v123
	v_exp_f32_e32 v101, v101
	v_and_b32_e32 v125, 64, v140
	v_add_f32_e32 v100, 1.0, v100
	v_rcp_f32_e32 v148, v100
	v_add_f32_e32 v100, 1.0, v101
	v_rcp_f32_e32 v149, v100
	v_xor_b32_e32 v113, 1, v140
	v_add_u32_e32 v107, 64, v125
	v_cmp_lt_i32_e32 vcc, v113, v107
	v_pk_mul_f32 v[122:123], v[122:123], v[148:149]
	v_lshlrev_b32_e32 v148, 16, v49
	v_and_b32_e32 v149, 0xffff0000, v49
	v_pk_fma_f32 v[146:147], v[98:99], v[148:149], v[146:147]
	v_lshlrev_b32_e32 v148, 16, v42
	v_and_b32_e32 v149, 0xffff0000, v42
	v_pk_fma_f32 v[138:139], v[96:97], v[148:149], v[138:139]
	v_lshlrev_b32_e32 v148, 16, v5
	v_and_b32_e32 v149, 0xffff0000, v5
	v_cndmask_b32_e32 v100, v140, v113, vcc
	v_mul_f32_e32 v113, 0xbfb8aa3b, v126
	v_pk_fma_f32 v[98:99], v[98:99], v[148:149], v[120:121]
	v_lshlrev_b32_e32 v120, 16, v4
	v_and_b32_e32 v121, 0xffff0000, v4
	v_exp_f32_e32 v113, v113
	v_pk_fma_f32 v[96:97], v[96:97], v[120:121], v[118:119]
	v_mul_f32_e32 v118, 0xbfb8aa3b, v127
	v_exp_f32_e32 v121, v118
	v_lshlrev_b32_e32 v148, 16, v57
	v_and_b32_e32 v149, 0xffff0000, v57
	v_pk_fma_f32 v[146:147], v[110:111], v[148:149], v[146:147]
	v_lshlrev_b32_e32 v148, 16, v17
	v_and_b32_e32 v149, 0xffff0000, v17
	v_pk_fma_f32 v[146:147], v[116:117], v[148:149], v[146:147]
	v_lshlrev_b32_e32 v148, 16, v48
	v_and_b32_e32 v149, 0xffff0000, v48
	v_add_f32_e32 v113, 1.0, v113
	v_pk_fma_f32 v[138:139], v[108:109], v[148:149], v[138:139]
	v_lshlrev_b32_e32 v148, 16, v16
	v_and_b32_e32 v149, 0xffff0000, v16
	v_rcp_f32_e32 v120, v113
	v_add_f32_e32 v113, 1.0, v121
	v_pk_fma_f32 v[138:139], v[114:115], v[148:149], v[138:139]
	v_lshlrev_b32_e32 v148, 16, v9
	v_and_b32_e32 v149, 0xffff0000, v9
	v_rcp_f32_e32 v121, v113
	v_mul_f32_e32 v113, 0xbfb8aa3b, v146
	v_pk_fma_f32 v[98:99], v[110:111], v[148:149], v[98:99]
	v_lshlrev_b32_e32 v110, 16, v8
	v_and_b32_e32 v111, 0xffff0000, v8
	v_exp_f32_e32 v113, v113
	v_mul_f32_e32 v125, 0xbfb8aa3b, v147
	v_pk_fma_f32 v[96:97], v[108:109], v[110:111], v[96:97]
	v_mul_f32_e32 v108, 0xbfb8aa3b, v138
	v_mul_f32_e32 v109, 0xbfb8aa3b, v139
	v_exp_f32_e32 v125, v125
	v_exp_f32_e32 v108, v108
	v_exp_f32_e32 v109, v109
	v_add_f32_e32 v113, 1.0, v113
	v_pk_mul_f32 v[120:121], v[126:127], v[120:121]
	v_rcp_f32_e32 v126, v113
	v_add_f32_e32 v113, 1.0, v125
	v_add_f32_e32 v108, 1.0, v108
	v_add_f32_e32 v109, 1.0, v109
	v_rcp_f32_e32 v127, v113
	v_rcp_f32_e32 v108, v108
	v_rcp_f32_e32 v109, v109
	v_mul_f32_e32 v113, 0xbfb8aa3b, v102
	v_exp_f32_e32 v113, v113
	v_mul_f32_e32 v125, 0xbfb8aa3b, v103
	v_exp_f32_e32 v125, v125
	v_pk_mul_f32 v[108:109], v[138:139], v[108:109]
	v_lshlrev_b32_e32 v138, 16, v13
	v_and_b32_e32 v139, 0xffff0000, v13
	v_pk_fma_f32 v[98:99], v[116:117], v[138:139], v[98:99]
	v_lshlrev_b32_e32 v116, 16, v12
	v_and_b32_e32 v117, 0xffff0000, v12
	v_add_f32_e32 v113, 1.0, v113
	v_pk_fma_f32 v[96:97], v[114:115], v[116:117], v[96:97]
	v_rcp_f32_e32 v116, v113
	v_add_f32_e32 v113, 1.0, v125
	v_rcp_f32_e32 v117, v113
	v_mul_f32_e32 v113, 0xbfb8aa3b, v136
	v_exp_f32_e32 v113, v113
	v_mul_f32_e32 v125, 0xbfb8aa3b, v137
	v_exp_f32_e32 v125, v125
	v_pk_mul_f32 v[102:103], v[102:103], v[116:117]
	v_add_f32_e32 v113, 1.0, v113
	v_mul_f32_e32 v117, 0xbfb8aa3b, v98
	v_rcp_f32_e32 v116, v113
	v_add_f32_e32 v113, 1.0, v125
	v_exp_f32_e32 v125, v117
	v_mul_f32_e32 v117, 0xbfb8aa3b, v99
	v_exp_f32_e32 v130, v117
	v_rcp_f32_e32 v117, v113
	v_add_f32_e32 v113, 1.0, v125
	v_mul_f32_e32 v125, 0xbfb8aa3b, v96
	v_rcp_f32_e32 v138, v113
	v_add_f32_e32 v113, 1.0, v130
	v_exp_f32_e32 v125, v125
	v_mul_f32_e32 v130, 0xbfb8aa3b, v97
	v_exp_f32_e32 v130, v130
	v_rcp_f32_e32 v139, v113
	v_add_f32_e32 v113, 1.0, v125
	v_rcp_f32_e32 v148, v113
	v_add_f32_e32 v113, 1.0, v130
	v_rcp_f32_e32 v149, v113
	v_pk_mul_f32 v[126:127], v[146:147], v[126:127]
	v_pk_mul_f32 v[114:115], v[108:109], v[108:109]
	v_pk_mul_f32 v[150:151], v[98:99], v[138:139]
	v_pk_mul_f32 v[148:149], v[96:97], v[148:149]
	v_pk_mul_f32 v[146:147], v[126:127], v[126:127]
	v_pk_mul_f32 v[96:97], v[148:149], v[148:149]
	v_mov_b32_e32 v99, v114
	v_mov_b32_e32 v98, v96
	v_mov_b32_e32 v114, v97
	v_pk_mul_f32 v[96:97], v[150:151], v[150:151]
	v_pk_mul_f32 v[136:137], v[136:137], v[116:117]
	v_pk_add_f32 v[98:99], v[98:99], v[114:115]
	v_mov_b32_e32 v114, v96
	v_mov_b32_e32 v115, v146
	v_pk_mul_f32 v[110:111], v[120:121], v[120:121]
	v_pk_add_f32 v[98:99], v[98:99], v[114:115]
	v_pk_mul_f32 v[114:115], v[136:137], v[136:137]
	v_mov_b32_e32 v146, v97
	v_pk_add_f32 v[96:97], v[98:99], v[146:147]
	v_mov_b32_e32 v98, v114
	v_mov_b32_e32 v99, v110
	v_pk_mul_f32 v[118:119], v[122:123], v[122:123]
	v_pk_mul_f32 v[116:117], v[102:103], v[102:103]
	v_pk_add_f32 v[96:97], v[96:97], v[98:99]
	v_mov_b32_e32 v110, v115
	v_pk_add_f32 v[96:97], v[96:97], v[110:111]
	v_mov_b32_e32 v98, v116
	v_mov_b32_e32 v99, v118
	v_pk_add_f32 v[96:97], v[96:97], v[98:99]
	v_mov_b32_e32 v118, v117
	v_lshlrev_b32_e32 v101, 2, v100
	v_pk_add_f32 v[96:97], v[96:97], v[118:119]
	ds_bpermute_b32 v99, v101, v97
	ds_bpermute_b32 v98, v101, v96
	v_xor_b32_e32 v100, 2, v140
	v_cmp_lt_i32_e32 vcc, v100, v107
	v_lshl_add_u32 v104, v142, 4, 0
	v_mad_u64_u32 v[138:139], s[8:9], v128, s33, v[104:105]
	v_cndmask_b32_e32 v100, v140, v100, vcc
	v_lshlrev_b32_e32 v113, 2, v100
	s_waitcnt lgkmcnt(0)
	v_pk_add_f32 v[96:97], v[96:97], v[98:99]
	ds_bpermute_b32 v99, v113, v97
	ds_bpermute_b32 v98, v113, v96
	v_xor_b32_e32 v100, 4, v140
	v_cmp_lt_i32_e32 vcc, v100, v107
	s_add_i32 s6, 0, 0x1f800
	s_lshl_b64 s[28:29], s[4:5], 1
	v_cndmask_b32_e32 v100, v140, v100, vcc
	v_lshlrev_b32_e32 v115, 2, v100
	s_waitcnt lgkmcnt(0)
	v_pk_add_f32 v[96:97], v[96:97], v[98:99]
	ds_bpermute_b32 v99, v115, v97
	ds_bpermute_b32 v98, v115, v96
	v_xor_b32_e32 v100, 8, v140
	v_cmp_lt_i32_e32 vcc, v100, v107
	s_add_u32 s4, s42, s28
	s_addc_u32 s5, s43, s29
	v_cndmask_b32_e32 v100, v140, v100, vcc
	v_lshlrev_b32_e32 v116, 2, v100
	s_waitcnt lgkmcnt(0)
	v_pk_add_f32 v[96:97], v[96:97], v[98:99]
	ds_bpermute_b32 v99, v116, v97
	ds_bpermute_b32 v98, v116, v96
	v_add_u32_e32 v100, 0x200, v132
	v_ashrrev_i32_e32 v134, 4, v100
	v_lshlrev_b32_e32 v117, 2, v134
	v_add_u32_e32 v114, s7, v117
	s_waitcnt lgkmcnt(0)
	v_pk_add_f32 v[96:97], v[96:97], v[98:99]
	v_ashrrev_i32_e32 v133, 31, v132
	v_pk_add_f32 v[110:111], v[96:97], s[22:23] op_sel_hi:[1,0]
	v_lshl_add_u64 v[146:147], v[132:133], 4, s[4:5]
	v_mul_f32_e32 v96, 0x4b800000, v111
	v_cmp_gt_f32_e32 vcc, s36, v111
	v_lshlrev_b32_e32 v154, 16, v79
	v_and_b32_e32 v155, 0xffff0000, v79
	v_cndmask_b32_e32 v96, v111, v96, vcc
	v_rsq_f32_e32 v96, v96
	v_lshlrev_b32_e32 v160, 16, v83
	v_and_b32_e32 v161, 0xffff0000, v83
	v_lshlrev_b32_e32 v168, 16, v23
	v_mul_f32_e32 v97, 0x45800000, v96
	v_cndmask_b32_e32 v96, v96, v97, vcc
	v_mul_f32_e32 v96, 0x3db504f3, v96
	v_pk_mul_f32 v[108:109], v[108:109], v[96:97] op_sel_hi:[1,0]
	v_pk_mul_f32 v[126:127], v[126:127], v[96:97] op_sel_hi:[1,0]
	v_pk_mul_f32 v[120:121], v[120:121], v[96:97] op_sel_hi:[1,0]
	v_pk_mul_f32 v[122:123], v[122:123], v[96:97] op_sel_hi:[1,0]
	v_cvt_pk_bf16_f32 v96, v108, v109
	v_cvt_pk_bf16_f32 v97, v126, v127
	v_cvt_pk_bf16_f32 v98, v120, v121
	v_cvt_pk_bf16_f32 v99, v122, v123
	ds_write_b128 v138, v[96:99]
	v_mul_f32_e32 v98, 0x4b800000, v110
	v_cmp_gt_f32_e32 vcc, s36, v110
	v_pk_mul_f32 v[96:97], v[106:107], v[108:109] op_sel_hi:[0,1]
	v_cvt_pk_bf16_f32 v118, v96, v97
	v_cndmask_b32_e32 v98, v110, v98, vcc
	v_rsq_f32_e32 v98, v98
	v_pk_mul_f32 v[96:97], v[106:107], v[126:127] op_sel_hi:[0,1]
	v_cvt_pk_bf16_f32 v119, v96, v97
	v_pk_mul_f32 v[96:97], v[106:107], v[120:121] op_sel_hi:[0,1]
	v_cvt_pk_bf16_f32 v120, v96, v97
	v_mul_f32_e32 v96, 0x45800000, v98
	v_cndmask_b32_e32 v96, v98, v96, vcc
	v_mul_f32_e32 v96, 0x3db504f3, v96
	v_pk_mul_f32 v[122:123], v[106:107], v[122:123] op_sel_hi:[0,1]
	v_pk_mul_f32 v[108:109], v[148:149], v[96:97] op_sel_hi:[1,0]
	v_pk_mul_f32 v[110:111], v[150:151], v[96:97] op_sel_hi:[1,0]
	v_pk_mul_f32 v[106:107], v[136:137], v[96:97] op_sel_hi:[1,0]
	v_pk_mul_f32 v[102:103], v[102:103], v[96:97] op_sel_hi:[1,0]
	v_cvt_pk_bf16_f32 v96, v108, v109
	v_cvt_pk_bf16_f32 v97, v110, v111
	v_cvt_pk_bf16_f32 v98, v106, v107
	v_cvt_pk_bf16_f32 v99, v102, v103
	v_mad_u64_u32 v[136:137], s[8:9], v134, s33, v[104:105]
	ds_read_b32 v125, v114
	ds_write_b128 v136, v[96:99]
	ds_read_b128 v[96:99], v124 offset:2064
	v_cvt_pk_bf16_f32 v121, v122, v123
	global_store_dwordx4 v[146:147], v[118:121], off
	v_lshlrev_b32_e32 v122, 16, v71
	v_and_b32_e32 v123, 0xffff0000, v71
	v_lshlrev_b32_e32 v146, 16, v27
	v_and_b32_e32 v147, 0xffff0000, v27
	ds_read_b128 v[118:121], v124 offset:2048
	s_waitcnt lgkmcnt(1)
	v_pk_fma_f32 v[122:123], v[98:99], v[122:123], 0 op_sel_hi:[1,1,0]
	v_lshlrev_b32_e32 v126, 16, v80
	v_and_b32_e32 v127, 0xffff0000, v80
	v_pk_fma_f32 v[150:151], v[98:99], v[146:147], 0 op_sel_hi:[1,1,0]
	v_lshlrev_b32_e32 v98, 16, v26
	v_and_b32_e32 v99, 0xffff0000, v26
	v_pk_fma_f32 v[126:127], v[96:97], v[126:127], 0 op_sel_hi:[1,1,0]
	v_pk_fma_f32 v[152:153], v[96:97], v[98:99], 0 op_sel_hi:[1,1,0]
	ds_read_b128 v[96:99], v124 offset:2576
	ds_read_b128 v[146:149], v124 offset:2560
	v_and_b32_e32 v169, 0xffff0000, v23
	v_add_u32_e32 v130, s6, v112
	v_add_u32_e32 v137, s6, v117
	s_waitcnt lgkmcnt(1)
	v_pk_fma_f32 v[122:123], v[98:99], v[154:155], v[122:123]
	v_lshlrev_b32_e32 v154, 16, v84
	v_and_b32_e32 v155, 0xffff0000, v84
	v_pk_fma_f32 v[126:127], v[96:97], v[154:155], v[126:127]
	v_lshlrev_b32_e32 v154, 16, v31
	v_and_b32_e32 v155, 0xffff0000, v31
	v_pk_fma_f32 v[154:155], v[98:99], v[154:155], v[150:151]
	v_lshlrev_b32_e32 v98, 16, v30
	v_and_b32_e32 v99, 0xffff0000, v30
	v_pk_fma_f32 v[158:159], v[96:97], v[98:99], v[152:153]
	ds_read_b128 v[96:99], v124 offset:3088
	ds_read_b128 v[150:153], v124 offset:3072
	s_cmp_lt_i32 s31, 0
	s_waitcnt lgkmcnt(1)
	v_pk_fma_f32 v[122:123], v[98:99], v[160:161], v[122:123]
	v_lshlrev_b32_e32 v160, 16, v88
	v_and_b32_e32 v161, 0xffff0000, v88
	v_pk_fma_f32 v[126:127], v[96:97], v[160:161], v[126:127]
	v_lshlrev_b32_e32 v160, 16, v35
	v_and_b32_e32 v161, 0xffff0000, v35
	v_pk_fma_f32 v[154:155], v[98:99], v[160:161], v[154:155]
	v_lshlrev_b32_e32 v98, 16, v34
	v_and_b32_e32 v99, 0xffff0000, v34
	v_pk_fma_f32 v[162:163], v[96:97], v[98:99], v[158:159]
	ds_read_b128 v[96:99], v124 offset:3600
	ds_read_b128 v[158:161], v124 offset:3584
	ds_read_b32 v112, v105
	s_waitcnt lgkmcnt(2)
	v_pk_fma_f32 v[122:123], v[98:99], v[168:169], v[122:123]
	v_lshlrev_b32_e32 v168, 16, v22
	v_and_b32_e32 v169, 0xffff0000, v22
	v_pk_fma_f32 v[126:127], v[96:97], v[168:169], v[126:127]
	v_lshlrev_b32_e32 v168, 16, v39
	v_and_b32_e32 v169, 0xffff0000, v39
	v_pk_fma_f32 v[154:155], v[98:99], v[168:169], v[154:155]
	v_lshlrev_b32_e32 v98, 16, v38
	v_and_b32_e32 v99, 0xffff0000, v38
	v_pk_fma_f32 v[162:163], v[96:97], v[98:99], v[162:163]
	v_lshlrev_b32_e32 v96, 16, v65
	v_and_b32_e32 v97, 0xffff0000, v65
	v_lshlrev_b32_e32 v168, 16, v25
	v_and_b32_e32 v169, 0xffff0000, v25
	v_pk_fma_f32 v[96:97], v[120:121], v[96:97], 0 op_sel_hi:[1,1,0]
	v_lshlrev_b32_e32 v98, 16, v62
	v_and_b32_e32 v99, 0xffff0000, v62
	v_pk_fma_f32 v[120:121], v[120:121], v[168:169], 0 op_sel_hi:[1,1,0]
	v_lshlrev_b32_e32 v168, 16, v24
	v_and_b32_e32 v169, 0xffff0000, v24
	v_pk_fma_f32 v[98:99], v[118:119], v[98:99], 0 op_sel_hi:[1,1,0]
	v_pk_fma_f32 v[118:119], v[118:119], v[168:169], 0 op_sel_hi:[1,1,0]
	v_lshlrev_b32_e32 v168, 16, v77
	v_and_b32_e32 v169, 0xffff0000, v77
	v_pk_fma_f32 v[96:97], v[148:149], v[168:169], v[96:97]
	v_lshlrev_b32_e32 v168, 16, v70
	v_and_b32_e32 v169, 0xffff0000, v70
	v_pk_fma_f32 v[98:99], v[146:147], v[168:169], v[98:99]
	v_lshlrev_b32_e32 v168, 16, v29
	v_and_b32_e32 v169, 0xffff0000, v29
	v_pk_fma_f32 v[120:121], v[148:149], v[168:169], v[120:121]
	v_lshlrev_b32_e32 v148, 16, v28
	v_and_b32_e32 v149, 0xffff0000, v28
	v_pk_fma_f32 v[118:119], v[146:147], v[148:149], v[118:119]
	v_lshlrev_b32_e32 v146, 16, v81
	v_and_b32_e32 v147, 0xffff0000, v81
	v_pk_fma_f32 v[96:97], v[152:153], v[146:147], v[96:97]
	v_lshlrev_b32_e32 v146, 16, v76
	v_and_b32_e32 v147, 0xffff0000, v76
	v_pk_fma_f32 v[98:99], v[150:151], v[146:147], v[98:99]
	v_lshlrev_b32_e32 v146, 16, v33
	v_and_b32_e32 v147, 0xffff0000, v33
	v_pk_fma_f32 v[120:121], v[152:153], v[146:147], v[120:121]
	v_lshlrev_b32_e32 v146, 16, v32
	v_and_b32_e32 v147, 0xffff0000, v32
	v_pk_fma_f32 v[118:119], v[150:151], v[146:147], v[118:119]
	v_lshlrev_b32_e32 v146, 16, v21
	v_and_b32_e32 v147, 0xffff0000, v21
	s_waitcnt lgkmcnt(1)
	v_pk_fma_f32 v[146:147], v[160:161], v[146:147], v[96:97]
	v_lshlrev_b32_e32 v96, 16, v20
	v_and_b32_e32 v97, 0xffff0000, v20
	v_pk_fma_f32 v[148:149], v[158:159], v[96:97], v[98:99]
	v_lshlrev_b32_e32 v96, 16, v37
	v_and_b32_e32 v97, 0xffff0000, v37
	v_pk_fma_f32 v[120:121], v[160:161], v[96:97], v[120:121]
	v_lshlrev_b32_e32 v96, 16, v36
	v_and_b32_e32 v97, 0xffff0000, v36
	v_pk_fma_f32 v[118:119], v[158:159], v[96:97], v[118:119]
	v_mul_f32_e32 v96, 0x3fb8aa3b, v125
	v_exp_f32_e32 v104, v96
	s_nop 0
	v_pk_mul_f32 v[96:97], v[104:105], v[108:109] op_sel_hi:[0,1]
	v_pk_mul_f32 v[98:99], v[104:105], v[110:111] op_sel_hi:[0,1]
	v_cvt_pk_bf16_f32 v96, v96, v97
	v_cvt_pk_bf16_f32 v97, v98, v99
	v_pk_mul_f32 v[98:99], v[104:105], v[106:107] op_sel_hi:[0,1]
	v_cvt_pk_bf16_f32 v98, v98, v99
	v_pk_mul_f32 v[102:103], v[104:105], v[102:103] op_sel_hi:[0,1]
	v_mul_f32_e32 v99, 0xbfb8aa3b, v122
	v_mul_f32_e32 v104, 0xbfb8aa3b, v123
	v_exp_f32_e32 v99, v99
	v_exp_f32_e32 v104, v104
	v_add_f32_e32 v99, 1.0, v99
	v_add_f32_e32 v104, 1.0, v104
	v_rcp_f32_e32 v106, v99
	v_rcp_f32_e32 v107, v104
	v_mul_f32_e32 v99, 0xbfb8aa3b, v126
	v_mul_f32_e32 v104, 0xbfb8aa3b, v127
	v_exp_f32_e32 v99, v99
	v_exp_f32_e32 v104, v104
	v_pk_mul_f32 v[106:107], v[122:123], v[106:107]
	v_add_f32_e32 v99, 1.0, v99
	v_add_f32_e32 v104, 1.0, v104
	v_rcp_f32_e32 v108, v99
	v_rcp_f32_e32 v109, v104
	v_mul_f32_e32 v99, 0xbfb8aa3b, v146
	v_mul_f32_e32 v104, 0xbfb8aa3b, v147
	v_exp_f32_e32 v99, v99
	v_exp_f32_e32 v104, v104
	v_pk_mul_f32 v[108:109], v[126:127], v[108:109]
	v_add_f32_e32 v99, 1.0, v99
	v_add_f32_e32 v104, 1.0, v104
	v_rcp_f32_e32 v110, v99
	v_rcp_f32_e32 v111, v104
	v_mul_f32_e32 v99, 0xbfb8aa3b, v148
	v_mul_f32_e32 v104, 0xbfb8aa3b, v149
	v_exp_f32_e32 v99, v99
	v_exp_f32_e32 v104, v104
	v_pk_mul_f32 v[110:111], v[146:147], v[110:111]
	v_add_f32_e32 v99, 1.0, v99
	v_add_f32_e32 v104, 1.0, v104
	v_rcp_f32_e32 v122, v99
	v_rcp_f32_e32 v123, v104
	v_mul_f32_e32 v99, 0xbfb8aa3b, v154
	v_mul_f32_e32 v104, 0xbfb8aa3b, v155
	v_exp_f32_e32 v99, v99
	v_exp_f32_e32 v104, v104
	v_pk_mul_f32 v[122:123], v[148:149], v[122:123]
	v_add_f32_e32 v99, 1.0, v99
	v_add_f32_e32 v104, 1.0, v104
	v_rcp_f32_e32 v126, v99
	v_rcp_f32_e32 v127, v104
	v_mul_f32_e32 v99, 0xbfb8aa3b, v162
	v_mul_f32_e32 v104, 0xbfb8aa3b, v163
	v_exp_f32_e32 v99, v99
	v_exp_f32_e32 v104, v104
	v_pk_mul_f32 v[126:127], v[154:155], v[126:127]
	v_add_f32_e32 v99, 1.0, v99
	v_add_f32_e32 v104, 1.0, v104
	v_rcp_f32_e32 v146, v99
	v_rcp_f32_e32 v147, v104
	v_mul_f32_e32 v99, 0xbfb8aa3b, v120
	v_mul_f32_e32 v104, 0xbfb8aa3b, v121
	v_exp_f32_e32 v99, v99
	v_exp_f32_e32 v104, v104
	v_pk_mul_f32 v[146:147], v[162:163], v[146:147]
	v_add_f32_e32 v99, 1.0, v99
	v_add_f32_e32 v104, 1.0, v104
	v_rcp_f32_e32 v148, v99
	v_rcp_f32_e32 v149, v104
	v_mul_f32_e32 v99, 0xbfb8aa3b, v118
	v_mul_f32_e32 v104, 0xbfb8aa3b, v119
	v_exp_f32_e32 v99, v99
	v_exp_f32_e32 v104, v104
	v_pk_mul_f32 v[120:121], v[120:121], v[148:149]
	v_add_f32_e32 v99, 1.0, v99
	v_add_f32_e32 v104, 1.0, v104
	v_rcp_f32_e32 v148, v99
	v_rcp_f32_e32 v149, v104
	v_cvt_pk_bf16_f32 v99, v102, v103
	v_pk_mul_f32 v[118:119], v[118:119], v[148:149]
	v_pk_mul_f32 v[148:149], v[122:123], v[122:123]
	v_pk_mul_f32 v[150:151], v[118:119], v[118:119]
	v_mov_b32_e32 v153, v148
	v_mov_b32_e32 v152, v150
	v_mov_b32_e32 v148, v151
	v_pk_add_f32 v[148:149], v[152:153], v[148:149]
	v_pk_mul_f32 v[150:151], v[110:111], v[110:111]
	v_pk_mul_f32 v[152:153], v[120:121], v[120:121]
	v_mov_b32_e32 v155, v150
	v_mov_b32_e32 v154, v152
	v_pk_add_f32 v[148:149], v[148:149], v[154:155]
	v_mov_b32_e32 v150, v153
	v_pk_add_f32 v[148:149], v[148:149], v[150:151]
	v_pk_mul_f32 v[150:151], v[108:109], v[108:109]
	v_pk_mul_f32 v[152:153], v[146:147], v[146:147]
	v_mov_b32_e32 v155, v150
	v_mov_b32_e32 v154, v152
	v_pk_add_f32 v[148:149], v[148:149], v[154:155]
	v_mov_b32_e32 v150, v153
	v_pk_add_f32 v[148:149], v[148:149], v[150:151]
	v_pk_mul_f32 v[150:151], v[106:107], v[106:107]
	v_pk_mul_f32 v[152:153], v[126:127], v[126:127]
	v_mov_b32_e32 v155, v150
	v_mov_b32_e32 v154, v152
	v_pk_add_f32 v[148:149], v[148:149], v[154:155]
	v_mov_b32_e32 v150, v153
	v_pk_add_f32 v[148:149], v[148:149], v[150:151]
	ds_bpermute_b32 v151, v101, v149
	ds_bpermute_b32 v150, v101, v148
	v_ashrrev_i32_e32 v101, 31, v100
	v_lshl_add_u64 v[100:101], v[100:101], 4, s[4:5]
	global_store_dwordx4 v[100:101], v[96:99], off
	v_lshlrev_b32_e32 v152, 16, v87
	s_waitcnt lgkmcnt(0)
	v_pk_add_f32 v[148:149], v[148:149], v[150:151]
	ds_bpermute_b32 v151, v113, v149
	ds_bpermute_b32 v150, v113, v148
	ds_read_b32 v113, v130
	v_mul_f32_e32 v112, 0x3fb8aa3b, v112
	v_exp_f32_e32 v112, v112
	v_and_b32_e32 v153, 0xffff0000, v87
	s_waitcnt lgkmcnt(1)
	v_pk_add_f32 v[148:149], v[148:149], v[150:151]
	ds_bpermute_b32 v151, v115, v149
	ds_bpermute_b32 v150, v115, v148
	s_waitcnt lgkmcnt(2)
	v_mul_f32_e32 v100, v113, v112
	s_waitcnt lgkmcnt(0)
	v_pk_add_f32 v[102:103], v[148:149], v[150:151]
	ds_bpermute_b32 v105, v116, v103
	ds_bpermute_b32 v104, v116, v102
	s_waitcnt vmcnt(6)
	v_lshlrev_b32_e32 v148, 16, v44
	v_and_b32_e32 v149, 0xffff0000, v44
	v_lshlrev_b32_e32 v150, 16, v85
	v_and_b32_e32 v151, 0xffff0000, v85
	s_waitcnt lgkmcnt(0)
	v_pk_add_f32 v[102:103], v[102:103], v[104:105]
	s_nop 0
	v_pk_add_f32 v[102:103], v[102:103], s[22:23] op_sel_hi:[1,0]
	s_nop 0
	v_mul_f32_e32 v104, 0x4b800000, v103
	v_cmp_gt_f32_e32 vcc, s36, v103
	s_nop 1
	v_cndmask_b32_e32 v103, v103, v104, vcc
	v_rsq_f32_e32 v103, v103
	s_nop 0
	v_mul_f32_e32 v96, 0x45800000, v103
	v_cndmask_b32_e32 v96, v103, v96, vcc
	v_pk_mul_f32 v[104:105], v[122:123], v[96:97] op_sel_hi:[1,0]
	v_pk_mul_f32 v[110:111], v[110:111], v[96:97] op_sel_hi:[1,0]
	v_pk_mul_f32 v[108:109], v[108:109], v[96:97] op_sel_hi:[1,0]
	v_pk_mul_f32 v[106:107], v[106:107], v[96:97] op_sel_hi:[1,0]
	v_cvt_pk_bf16_f32 v96, v104, v105
	v_cvt_pk_bf16_f32 v97, v110, v111
	v_cvt_pk_bf16_f32 v98, v108, v109
	v_cvt_pk_bf16_f32 v99, v106, v107
	ds_write_b128 v138, v[96:99] offset:17408
	v_pk_mul_f32 v[96:97], v[100:101], v[104:105] op_sel_hi:[0,1]
	v_pk_mul_f32 v[98:99], v[100:101], v[110:111] op_sel_hi:[0,1]
	v_cvt_pk_bf16_f32 v96, v96, v97
	v_cvt_pk_bf16_f32 v97, v98, v99
	v_pk_mul_f32 v[98:99], v[100:101], v[108:109] op_sel_hi:[0,1]
	v_pk_mul_f32 v[100:101], v[100:101], v[106:107] op_sel_hi:[0,1]
	v_cvt_pk_bf16_f32 v98, v98, v99
	v_cvt_pk_bf16_f32 v99, v100, v101
	ds_write_b128 v138, v[96:99] offset:52224
	ds_read_b32 v96, v114
	ds_read_b32 v108, v137
	v_mul_f32_e32 v97, 0x4b800000, v102
	v_cmp_gt_f32_e32 vcc, s36, v102
	s_waitcnt lgkmcnt(1)
	v_mul_f32_e32 v96, 0x3fb8aa3b, v96
	v_cndmask_b32_e32 v97, v102, v97, vcc
	v_rsq_f32_e32 v97, v97
	v_exp_f32_e32 v109, v96
	v_mul_f32_e32 v96, 0x45800000, v97
	v_cndmask_b32_e32 v96, v97, v96, vcc
	v_pk_mul_f32 v[100:101], v[118:119], v[96:97] op_sel_hi:[1,0]
	v_pk_mul_f32 v[102:103], v[120:121], v[96:97] op_sel_hi:[1,0]
	v_pk_mul_f32 v[104:105], v[146:147], v[96:97] op_sel_hi:[1,0]
	v_pk_mul_f32 v[106:107], v[126:127], v[96:97] op_sel_hi:[1,0]
	v_cvt_pk_bf16_f32 v96, v100, v101
	v_cvt_pk_bf16_f32 v97, v102, v103
	v_cvt_pk_bf16_f32 v98, v104, v105
	v_cvt_pk_bf16_f32 v99, v106, v107
	s_waitcnt lgkmcnt(0)
	v_mul_f32_e32 v108, v108, v109
	ds_write_b128 v136, v[96:99] offset:17408
	v_pk_mul_f32 v[96:97], v[108:109], v[100:101] op_sel_hi:[0,1]
	v_pk_mul_f32 v[98:99], v[108:109], v[102:103] op_sel_hi:[0,1]
	v_cvt_pk_bf16_f32 v96, v96, v97
	v_cvt_pk_bf16_f32 v97, v98, v99
	v_pk_mul_f32 v[98:99], v[108:109], v[104:105] op_sel_hi:[0,1]
	v_pk_mul_f32 v[100:101], v[108:109], v[106:107] op_sel_hi:[0,1]
	v_cvt_pk_bf16_f32 v98, v98, v99
	v_cvt_pk_bf16_f32 v99, v100, v101
	ds_write_b128 v136, v[96:99] offset:52224
	ds_read_b128 v[120:123], v124 offset:4096
	ds_read_b128 v[96:99], v124 offset:4112
	ds_read_b128 v[112:115], v124 offset:4608
	ds_read_b128 v[100:103], v124 offset:5120
	ds_read_b128 v[108:111], v124 offset:5632
	v_lshlrev_b32_e32 v104, 16, v78
	v_and_b32_e32 v105, 0xffff0000, v78
	s_waitcnt lgkmcnt(4)
	v_pk_fma_f32 v[116:117], v[120:121], v[104:105], 0 op_sel_hi:[1,1,0]
	v_lshlrev_b32_e32 v118, 16, v82
	v_and_b32_e32 v119, 0xffff0000, v82
	s_waitcnt lgkmcnt(2)
	v_pk_fma_f32 v[126:127], v[112:113], v[118:119], v[116:117]
	v_lshlrev_b32_e32 v146, 16, v86
	v_and_b32_e32 v147, 0xffff0000, v86
	s_waitcnt lgkmcnt(1)
	v_pk_fma_f32 v[146:147], v[100:101], v[146:147], v[126:127]
	v_pk_fma_f32 v[150:151], v[122:123], v[150:151], 0 op_sel_hi:[1,1,0]
	s_waitcnt lgkmcnt(0)
	v_pk_fma_f32 v[146:147], v[108:109], v[148:149], v[146:147]
	ds_read_b128 v[104:107], v124 offset:4624
	ds_read_b128 v[116:119], v124 offset:5136
	v_mul_f32_e32 v139, 0xbfb8aa3b, v147
	v_mul_f32_e32 v148, 0xbfb8aa3b, v146
	v_exp_f32_e32 v139, v139
	v_exp_f32_e32 v148, v148
	ds_read_b128 v[124:127], v124 offset:5648
	ds_read_b32 v130, v130
	v_add_f32_e32 v139, 1.0, v139
	v_add_f32_e32 v148, 1.0, v148
	v_rcp_f32_e32 v149, v139
	v_rcp_f32_e32 v148, v148
	v_pk_fma_f32 v[152:153], v[98:99], v[152:153], 0 op_sel_hi:[1,1,0]
	v_pk_mul_f32 v[146:147], v[146:147], v[148:149]
	v_lshlrev_b32_e32 v148, 16, v89
	v_and_b32_e32 v149, 0xffff0000, v89
	v_pk_fma_f32 v[148:149], v[114:115], v[148:149], v[150:151]
	v_lshlrev_b32_e32 v150, 16, v93
	v_and_b32_e32 v151, 0xffff0000, v93
	v_pk_fma_f32 v[148:149], v[102:103], v[150:151], v[148:149]
	v_lshlrev_b32_e32 v150, 16, v45
	v_and_b32_e32 v151, 0xffff0000, v45
	v_pk_fma_f32 v[148:149], v[110:111], v[150:151], v[148:149]
	s_waitcnt lgkmcnt(0)
	v_pk_mul_f32 v[146:147], v[130:131], v[146:147] op_sel_hi:[0,1]
	v_mul_f32_e32 v139, 0xbfb8aa3b, v149
	v_mul_f32_e32 v150, 0xbfb8aa3b, v148
	v_exp_f32_e32 v139, v139
	v_exp_f32_e32 v150, v150
	v_cvt_pk_bf16_f32 v146, v146, v147
	v_add_f32_e32 v139, 1.0, v139
	v_add_f32_e32 v150, 1.0, v150
	v_rcp_f32_e32 v151, v139
	v_rcp_f32_e32 v150, v150
	s_nop 0
	v_pk_mul_f32 v[148:149], v[148:149], v[150:151]
	s_nop 0
	v_pk_mul_f32 v[148:149], v[130:131], v[148:149] op_sel_hi:[0,1]
	v_lshlrev_b32_e32 v150, 16, v90
	v_and_b32_e32 v151, 0xffff0000, v90
	v_cvt_pk_bf16_f32 v147, v148, v149
	v_lshlrev_b32_e32 v148, 16, v92
	v_and_b32_e32 v149, 0xffff0000, v92
	v_pk_fma_f32 v[150:151], v[96:97], v[150:151], 0 op_sel_hi:[1,1,0]
	s_nop 0
	v_pk_fma_f32 v[148:149], v[104:105], v[148:149], v[150:151]
	v_lshlrev_b32_e32 v150, 16, v94
	v_and_b32_e32 v151, 0xffff0000, v94
	v_pk_fma_f32 v[148:149], v[116:117], v[150:151], v[148:149]
	v_lshlrev_b32_e32 v150, 16, v46
	v_and_b32_e32 v151, 0xffff0000, v46
	v_pk_fma_f32 v[148:149], v[124:125], v[150:151], v[148:149]
	s_nop 0
	v_mul_f32_e32 v139, 0xbfb8aa3b, v149
	v_mul_f32_e32 v150, 0xbfb8aa3b, v148
	v_exp_f32_e32 v139, v139
	v_exp_f32_e32 v150, v150
	v_add_f32_e32 v139, 1.0, v139
	v_add_f32_e32 v150, 1.0, v150
	v_rcp_f32_e32 v151, v139
	v_rcp_f32_e32 v150, v150
	s_nop 0
	v_pk_mul_f32 v[148:149], v[148:149], v[150:151]
	v_lshlrev_b32_e32 v150, 16, v91
	v_and_b32_e32 v151, 0xffff0000, v91
	v_pk_fma_f32 v[150:151], v[106:107], v[150:151], v[152:153]
	v_lshlrev_b32_e32 v152, 16, v95
	v_and_b32_e32 v153, 0xffff0000, v95
	v_pk_fma_f32 v[150:151], v[118:119], v[152:153], v[150:151]
	v_lshlrev_b32_e32 v152, 16, v47
	v_and_b32_e32 v153, 0xffff0000, v47
	v_pk_mul_f32 v[148:149], v[130:131], v[148:149] op_sel_hi:[0,1]
	v_pk_fma_f32 v[150:151], v[126:127], v[152:153], v[150:151]
	v_cvt_pk_bf16_f32 v148, v148, v149
	v_mul_f32_e32 v139, 0xbfb8aa3b, v151
	v_mul_f32_e32 v149, 0xbfb8aa3b, v150
	v_exp_f32_e32 v139, v139
	v_exp_f32_e32 v149, v149
	v_add_f32_e32 v139, 1.0, v139
	v_add_f32_e32 v149, 1.0, v149
	v_rcp_f32_e32 v153, v139
	v_rcp_f32_e32 v152, v149
	s_waitcnt vmcnt(5)
	v_and_b32_e32 v139, 0xffff0000, v52
	v_pk_mul_f32 v[150:151], v[150:151], v[152:153]
	s_nop 0
	v_pk_mul_f32 v[150:151], v[130:131], v[150:151] op_sel_hi:[0,1]
	v_cvt_pk_bf16_f32 v149, v150, v151
	ds_write_b128 v138, v[146:149] offset:34816
	v_lshlrev_b32_e32 v138, 16, v52
	s_waitcnt vmcnt(4)
	v_lshlrev_b32_e32 v146, 16, v58
	v_and_b32_e32 v147, 0xffff0000, v58
	v_pk_fma_f32 v[120:121], v[120:121], v[138:139], 0 op_sel_hi:[1,1,0]
	s_nop 0
	v_pk_fma_f32 v[112:113], v[112:113], v[146:147], v[120:121]
	s_waitcnt vmcnt(3)
	v_lshlrev_b32_e32 v120, 16, v66
	v_and_b32_e32 v121, 0xffff0000, v66
	v_pk_fma_f32 v[100:101], v[100:101], v[120:121], v[112:113]
	s_waitcnt vmcnt(2)
	v_lshlrev_b32_e32 v112, 16, v72
	v_and_b32_e32 v113, 0xffff0000, v72
	v_pk_fma_f32 v[100:101], v[108:109], v[112:113], v[100:101]
	v_lshlrev_b32_e32 v108, 16, v53
	v_mul_f32_e32 v112, 0xbfb8aa3b, v101
	v_exp_f32_e32 v120, v112
	v_mul_f32_e32 v112, 0xbfb8aa3b, v100
	v_exp_f32_e32 v121, v112
	v_and_b32_e32 v109, 0xffff0000, v53
	v_pk_fma_f32 v[108:109], v[122:123], v[108:109], 0 op_sel_hi:[1,1,0]
	v_lshlrev_b32_e32 v112, 16, v59
	v_and_b32_e32 v113, 0xffff0000, v59
	v_pk_fma_f32 v[108:109], v[114:115], v[112:113], v[108:109]
	v_add_f32_e32 v113, 1.0, v120
	v_rcp_f32_e32 v115, v113
	v_add_f32_e32 v113, 1.0, v121
	v_lshlrev_b32_e32 v120, 16, v67
	v_and_b32_e32 v121, 0xffff0000, v67
	v_lshlrev_b32_e32 v122, 16, v73
	v_and_b32_e32 v123, 0xffff0000, v73
	v_pk_fma_f32 v[102:103], v[102:103], v[120:121], v[108:109]
	v_rcp_f32_e32 v114, v113
	v_pk_fma_f32 v[102:103], v[110:111], v[122:123], v[102:103]
	ds_read_b32 v112, v137
	v_mul_f32_e32 v108, 0xbfb8aa3b, v103
	v_exp_f32_e32 v108, v108
	v_mul_f32_e32 v109, 0xbfb8aa3b, v102
	v_exp_f32_e32 v110, v109
	v_and_b32_e32 v111, 0xffff0000, v60
	v_add_f32_e32 v108, 1.0, v108
	v_rcp_f32_e32 v109, v108
	v_add_f32_e32 v108, 1.0, v110
	v_rcp_f32_e32 v108, v108
	v_lshlrev_b32_e32 v110, 16, v60
	v_pk_mul_f32 v[100:101], v[100:101], v[114:115]
	v_lshlrev_b32_e32 v114, 16, v68
	v_pk_mul_f32 v[102:103], v[102:103], v[108:109]
	v_lshlrev_b32_e32 v108, 16, v54
	v_and_b32_e32 v109, 0xffff0000, v54
	v_pk_fma_f32 v[96:97], v[96:97], v[108:109], 0 op_sel_hi:[1,1,0]
	v_and_b32_e32 v115, 0xffff0000, v68
	v_pk_fma_f32 v[96:97], v[104:105], v[110:111], v[96:97]
	v_lshlrev_b32_e32 v120, 16, v74
	v_and_b32_e32 v121, 0xffff0000, v74
	v_pk_fma_f32 v[96:97], v[116:117], v[114:115], v[96:97]
	s_waitcnt lgkmcnt(0)
	v_pk_mul_f32 v[100:101], v[100:101], v[112:113] op_sel_hi:[1,0]
	v_pk_fma_f32 v[96:97], v[124:125], v[120:121], v[96:97]
	v_cvt_pk_bf16_f32 v100, v100, v101
	v_mul_f32_e32 v101, 0xbfb8aa3b, v97
	v_exp_f32_e32 v104, v101
	v_mul_f32_e32 v101, 0xbfb8aa3b, v96
	v_exp_f32_e32 v105, v101
	v_pk_mul_f32 v[102:103], v[112:113], v[102:103] op_sel_hi:[0,1]
	v_cvt_pk_bf16_f32 v101, v102, v103
	v_add_f32_e32 v102, 1.0, v104
	v_rcp_f32_e32 v103, v102
	v_add_f32_e32 v102, 1.0, v105
	v_lshlrev_b32_e32 v104, 16, v55
	v_and_b32_e32 v105, 0xffff0000, v55
	v_lshlrev_b32_e32 v108, 16, v61
	v_and_b32_e32 v109, 0xffff0000, v61
	v_pk_fma_f32 v[98:99], v[98:99], v[104:105], 0 op_sel_hi:[1,1,0]
	v_lshlrev_b32_e32 v110, 16, v69
	v_and_b32_e32 v111, 0xffff0000, v69
	v_pk_fma_f32 v[98:99], v[106:107], v[108:109], v[98:99]
	v_lshlrev_b32_e32 v114, 16, v75
	v_and_b32_e32 v115, 0xffff0000, v75
	v_pk_fma_f32 v[98:99], v[118:119], v[110:111], v[98:99]
	v_rcp_f32_e32 v102, v102
	v_pk_fma_f32 v[98:99], v[126:127], v[114:115], v[98:99]
	v_lshlrev_b32_e32 v118, 4, v132
	v_mul_f32_e32 v104, 0xbfb8aa3b, v99
	v_exp_f32_e32 v104, v104
	v_mul_f32_e32 v105, 0xbfb8aa3b, v98
	v_exp_f32_e32 v106, v105
	v_pk_mul_f32 v[96:97], v[96:97], v[102:103]
	v_add_f32_e32 v104, 1.0, v104
	v_rcp_f32_e32 v105, v104
	v_add_f32_e32 v104, 1.0, v106
	v_rcp_f32_e32 v104, v104
	v_pk_mul_f32 v[96:97], v[112:113], v[96:97] op_sel_hi:[0,1]
	v_cvt_pk_bf16_f32 v102, v96, v97
	v_pk_mul_f32 v[96:97], v[98:99], v[104:105]
	s_nop 0
	v_pk_mul_f32 v[96:97], v[112:113], v[96:97] op_sel_hi:[0,1]
	v_cvt_pk_bf16_f32 v103, v96, v97
	ds_write_b128 v136, v[100:103] offset:34816
	s_cbranch_scc1 .LBB0_374
	s_lshr_b32 s20, s31, 8
	s_lshl_b32 s4, s31, 6
	s_and_b32 s30, s4, 0x7c0
	s_lshl_b64 s[6:7], s[20:21], 11
	s_or_b32 s4, s6, s30
	s_add_u32 s8, s4, -3
	s_addc_u32 s9, s7, 0x3ffff
	v_add_u32_e32 v8, s30, v134
	v_ashrrev_i32_e32 v135, 31, v134
	v_add_u32_e32 v11, s30, v128
	v_ashrrev_i32_e32 v129, 31, v128
	v_lshl_add_u64 v[0:1], s[8:9], 0, v[134:135]
	v_mov_b32_e32 v9, s4
	v_cmp_lt_i32_e64 s[4:5], 2, v8
	v_mov_b32_e32 v10, s7
	v_lshl_add_u64 v[4:5], s[8:9], 0, v[128:129]
	v_cmp_lt_i32_e64 s[6:7], 2, v11
	v_cndmask_b32_e64 v2, v9, v0, s[4:5]
	v_cndmask_b32_e64 v3, v10, v1, s[4:5]
	v_cndmask_b32_e64 v6, v9, v4, s[6:7]
	v_cndmask_b32_e64 v7, v10, v5, s[6:7]
	v_lshlrev_b64 v[6:7], 14, v[6:7]
	s_lshl_b32 s8, s31, 3
	v_lshlrev_b64 v[2:3], 14, v[2:3]
	v_lshl_add_u64 v[6:7], s[66:67], 0, v[6:7]
	s_and_b32 s20, s8, 0x700
	v_lshl_add_u64 v[2:3], s[66:67], 0, v[2:3]
	v_lshl_add_u64 v[6:7], v[6:7], 0, s[20:21]
	v_and_b32_e32 v130, 0xf0, v118
	v_lshl_add_u64 v[2:3], v[2:3], 0, s[20:21]
	v_lshl_add_u64 v[44:45], v[6:7], 0, v[130:131]
	v_lshl_add_u64 v[6:7], v[4:5], 0, 1
	v_cmp_lt_i32_e64 s[8:9], 1, v11
	v_lshl_add_u64 v[56:57], v[2:3], 0, v[130:131]
	v_lshl_add_u64 v[2:3], v[0:1], 0, 1
	v_cmp_lt_i32_e64 s[14:15], 1, v8
	v_cndmask_b32_e64 v6, v9, v6, s[8:9]
	v_cndmask_b32_e64 v7, v10, v7, s[8:9]
	v_cndmask_b32_e64 v2, v9, v2, s[14:15]
	v_cndmask_b32_e64 v3, v10, v3, s[14:15]
	v_lshlrev_b64 v[6:7], 14, v[6:7]
	v_lshlrev_b64 v[2:3], 14, v[2:3]
	v_lshl_add_u64 v[6:7], s[66:67], 0, v[6:7]
	v_lshl_add_u64 v[2:3], s[66:67], 0, v[2:3]
	v_lshl_add_u64 v[6:7], v[6:7], 0, s[20:21]
	v_lshl_add_u64 v[2:3], v[2:3], 0, s[20:21]
	v_lshl_add_u64 v[46:47], v[6:7], 0, v[130:131]
	v_lshl_add_u64 v[6:7], v[4:5], 0, 2
	v_cmp_lt_i32_e64 s[10:11], 0, v11
	v_lshl_add_u64 v[4:5], v[4:5], 0, 3
	v_cmp_lt_i32_e64 s[12:13], -1, v11
	v_lshl_add_u64 v[58:59], v[2:3], 0, v[130:131]
	v_lshl_add_u64 v[2:3], v[0:1], 0, 2
	v_cmp_lt_i32_e64 s[16:17], 0, v8
	v_lshl_add_u64 v[0:1], v[0:1], 0, 3
	v_cmp_lt_i32_e64 s[18:19], -1, v8
	v_cndmask_b32_e64 v6, v9, v6, s[10:11]
	v_cndmask_b32_e64 v7, v10, v7, s[10:11]
	v_cndmask_b32_e64 v4, v9, v4, s[12:13]
	v_cndmask_b32_e64 v5, v10, v5, s[12:13]
	v_cndmask_b32_e64 v2, v9, v2, s[16:17]
	v_cndmask_b32_e64 v3, v10, v3, s[16:17]
	v_cndmask_b32_e64 v0, v9, v0, s[18:19]
	v_cndmask_b32_e64 v1, v10, v1, s[18:19]
	v_lshlrev_b64 v[6:7], 14, v[6:7]
	v_lshlrev_b64 v[4:5], 14, v[4:5]
	v_lshlrev_b64 v[2:3], 14, v[2:3]
	v_lshlrev_b64 v[0:1], 14, v[0:1]
	v_lshl_add_u64 v[6:7], s[66:67], 0, v[6:7]
	v_lshl_add_u64 v[4:5], s[66:67], 0, v[4:5]
	v_lshl_add_u64 v[2:3], s[66:67], 0, v[2:3]
	v_lshl_add_u64 v[0:1], s[66:67], 0, v[0:1]
	v_lshl_add_u64 v[6:7], v[6:7], 0, s[20:21]
	v_lshl_add_u64 v[4:5], v[4:5], 0, s[20:21]
	v_lshl_add_u64 v[2:3], v[2:3], 0, s[20:21]
	v_lshl_add_u64 v[0:1], v[0:1], 0, s[20:21]
	v_lshl_add_u64 v[48:49], v[6:7], 0, v[130:131]
	v_lshl_add_u64 v[50:51], v[4:5], 0, v[130:131]
	v_lshl_add_u64 v[66:67], v[2:3], 0, v[130:131]
	v_lshl_add_u64 v[68:69], v[0:1], 0, v[130:131]
	global_load_dwordx4 v[40:43], v[44:45], off
	global_load_dwordx4 v[82:85], v[44:45], off offset:2048
	global_load_dwordx4 v[62:65], v[46:47], off
	global_load_dwordx4 v[76:79], v[46:47], off offset:2048
	global_load_dwordx4 v[180:183], v[48:49], off
	global_load_dwordx4 v[86:89], v[48:49], off offset:2048
	global_load_dwordx4 v[16:19], v[50:51], off
	global_load_dwordx4 v[20:23], v[50:51], off offset:2048
	global_load_dwordx4 v[0:3], v[56:57], off
	global_load_dwordx4 v[24:27], v[56:57], off offset:2048
	global_load_dwordx4 v[4:7], v[58:59], off
	global_load_dwordx4 v[28:31], v[58:59], off offset:2048
	global_load_dwordx4 v[8:11], v[66:67], off
	global_load_dwordx4 v[32:35], v[66:67], off offset:2048
	global_load_dwordx4 v[12:15], v[68:69], off
	global_load_dwordx4 v[36:39], v[68:69], off offset:2048
	v_add_co_u32_e32 v44, vcc, s37, v44
	v_mov_b32_e32 v129, 0
	s_nop 0
	v_addc_co_u32_e32 v45, vcc, 0, v45, vcc
	v_add_co_u32_e32 v46, vcc, s37, v46
	v_mov_b32_e32 v135, 0
	s_nop 0
	v_addc_co_u32_e32 v47, vcc, 0, v47, vcc
	global_load_dwordx4 v[92:95], v[44:45], off
	global_load_dwordx4 v[52:55], v[46:47], off
	v_add_co_u32_e32 v44, vcc, s37, v48
	s_nop 1
	v_addc_co_u32_e32 v45, vcc, 0, v49, vcc
	v_add_co_u32_e32 v46, vcc, s37, v50
	s_nop 1
	v_addc_co_u32_e32 v47, vcc, 0, v51, vcc
	v_add_co_u32_e32 v48, vcc, s37, v56
	global_load_dwordx4 v[176:179], v[44:45], off
	s_nop 0
	global_load_dwordx4 v[44:47], v[46:47], off
	v_addc_co_u32_e32 v49, vcc, 0, v57, vcc
	v_add_co_u32_e32 v50, vcc, s37, v58
	s_nop 1
	v_addc_co_u32_e32 v51, vcc, 0, v59, vcc
	global_load_dwordx4 v[172:175], v[48:49], off
	global_load_dwordx4 v[58:61], v[50:51], off
	v_add_co_u32_e32 v48, vcc, 0x1000, v66
	s_nop 1
	v_addc_co_u32_e32 v49, vcc, 0, v67, vcc
	v_add_co_u32_e32 v50, vcc, 0x1000, v68
	s_nop 1
	v_addc_co_u32_e32 v51, vcc, 0, v69, vcc
	global_load_dwordx4 v[66:69], v[48:49], off
	global_load_dwordx4 v[72:75], v[50:51], off
	s_and_saveexec_b64 s[34:35], s[2:3]
	s_cbranch_execz .LBB0_373
	s_lshr_b32 s20, s31, 5
	s_mov_b32 s31, s21
	s_lshl_b64 s[90:91], s[20:21], 11
	s_or_b64 s[30:31], s[90:91], s[30:31]
	v_lshl_add_u64 v[48:49], s[30:31], 0, v[132:133]
	v_lshlrev_b64 v[48:49], 2, v[48:49]
	v_lshl_add_u64 v[50:51], s[72:73], 0, v[48:49]
	v_lshl_add_u64 v[48:49], s[74:75], 0, v[48:49]
	global_load_dword v129, v[48:49], off
	global_load_dword v135, v[50:51], off
.LBB0_373:
	s_or_b64 exec, exec, s[34:35]



.LBB0_521:
	s_or_b64 exec, exec, s[2:3]
	v_or_b32_e32 v102, v96, v142
	s_movk_i32 s2, 0x440
	v_mad_u32_u24 v97, v121, s2, v102
	s_waitcnt lgkmcnt(0)
	s_barrier
	s_and_b32 s4, s96, 31
	s_lshl_b32 s4, s4, 6
	v_lshrrev_b32_e32 v170, 4, v198
	v_add_u32_e32 v170, s4, v170
	v_cmp_lt_i32_e64 s[6:7], 2, v170
	v_cmp_lt_i32_e64 s[8:9], 1, v170
	v_cmp_lt_i32_e64 s[10:11], 0, v170
	s_nop 1
	s_waitcnt vmcnt(23)
	v_cndmask_b32_e64 v43, 0, v43, s[6:7]
	v_cndmask_b32_e64 v50, 0, v42, s[6:7]
	v_cndmask_b32_e64 v41, 0, v41, s[6:7]
	v_cndmask_b32_e64 v40, 0, v40, s[6:7]
	s_waitcnt vmcnt(21)
	v_cndmask_b32_e64 v51, 0, v65, s[8:9]
	v_cndmask_b32_e64 v56, 0, v64, s[8:9]
	v_cndmask_b32_e64 v49, 0, v63, s[8:9]
	v_cndmask_b32_e64 v42, 0, v62, s[8:9]
	s_waitcnt vmcnt(19)
	v_cndmask_b32_e64 v63, 0, v183, s[10:11]
	v_cndmask_b32_e64 v64, 0, v182, s[10:11]
	v_cndmask_b32_e64 v57, 0, v181, s[10:11]
	v_cndmask_b32_e64 v48, 0, v180, s[10:11]
	s_waitcnt vmcnt(17)
	s_waitcnt vmcnt(15)
	s_waitcnt vmcnt(13)
	s_waitcnt vmcnt(11)
	s_waitcnt vmcnt(9)
	v_cndmask_b32_e64 v71, 0, v85, s[6:7]
	v_cndmask_b32_e64 v80, 0, v84, s[6:7]
	v_cndmask_b32_e64 v65, 0, v83, s[6:7]
	v_cndmask_b32_e64 v62, 0, v82, s[6:7]
	v_cndmask_b32_e64 v79, 0, v79, s[8:9]
	v_cndmask_b32_e64 v84, 0, v78, s[8:9]
	v_cndmask_b32_e64 v77, 0, v77, s[8:9]
	v_cndmask_b32_e64 v70, 0, v76, s[8:9]
	v_cndmask_b32_e64 v83, 0, v89, s[10:11]
	v_cndmask_b32_e64 v88, 0, v88, s[10:11]
	v_cndmask_b32_e64 v81, 0, v87, s[10:11]
	v_cndmask_b32_e64 v76, 0, v86, s[10:11]
	s_waitcnt vmcnt(8)
	s_waitcnt vmcnt(7)
	v_cndmask_b32_e64 v87, 0, v95, s[6:7]
	v_cndmask_b32_e64 v90, 0, v94, s[6:7]
	v_cndmask_b32_e64 v85, 0, v93, s[6:7]
	v_cndmask_b32_e64 v78, 0, v92, s[6:7]
	s_waitcnt vmcnt(6)
	v_cndmask_b32_e64 v91, 0, v55, s[8:9]
	v_cndmask_b32_e64 v92, 0, v54, s[8:9]
	v_cndmask_b32_e64 v89, 0, v53, s[8:9]
	v_cndmask_b32_e64 v82, 0, v52, s[8:9]
	s_waitcnt vmcnt(5)
	v_cndmask_b32_e64 v95, 0, v179, s[10:11]
	v_cndmask_b32_e64 v94, 0, v178, s[10:11]
	v_cndmask_b32_e64 v93, 0, v177, s[10:11]
	v_cndmask_b32_e64 v86, 0, v176, s[10:11]
	s_waitcnt vmcnt(4)
	s_waitcnt vmcnt(3)
	v_mov_b32_e32 v55, v175
	v_mov_b32_e32 v54, v174
	v_mov_b32_e32 v53, v173
	v_mov_b32_e32 v52, v172
	s_waitcnt vmcnt(2)
	s_waitcnt vmcnt(1)
	s_waitcnt vmcnt(0)
	v_lshl_add_u32 v97, v97, 1, 0
	ds_read_u16 v106, v97 offset:34816
	ds_read_u16 v107, v97 offset:35088
	ds_read_u16 v108, v97 offset:35360
	ds_read_u16 v109, v97 offset:35632
	ds_read_u16 v104, v97 offset:35904
	ds_read_u16 v110, v97 offset:36176
	ds_read_u16 v105, v97 offset:36448
	ds_read_u16 v111, v97 offset:36720
	ds_read_u16 v114, v97 offset:52224
	ds_read_u16 v122, v97 offset:52496
	ds_read_u16 v115, v97 offset:52768
	ds_read_u16 v123, v97 offset:53040
	ds_read_u16 v116, v97 offset:53312
	ds_read_u16 v124, v97 offset:53584
	ds_read_u16 v117, v97 offset:53856
	ds_read_u16 v125, v97 offset:54128
	ds_read_u16 v126, v97 offset:43520
	ds_read_u16 v127, v97 offset:43792
	ds_read_u16 v128, v97 offset:44064
	ds_read_u16 v133, v97 offset:44336
	ds_read_u16 v134, v97 offset:44608
	ds_read_u16 v146, v97 offset:44880
	ds_read_u16 v147, v97 offset:45152
	ds_read_u16 v148, v97 offset:45424
	ds_read_u16 v149, v97 offset:60928
	ds_read_u16 v150, v97 offset:61200
	ds_read_u16 v151, v97 offset:61472
	ds_read_u16 v152, v97 offset:61744
	ds_read_u16 v153, v97 offset:62016
	ds_read_u16 v154, v97 offset:62288
	ds_read_u16 v155, v97 offset:62560
	ds_read_u16 v157, v97 offset:62832
	v_mul_u32_u24_e32 v97, 0x90, v142
	v_add3_u32 v158, s1, v120, v97
	ds_read_b128 v[98:101], v158
	v_ashrrev_i32_e32 v103, 31, v102
	v_lshlrev_b64 v[120:121], 7, v[102:103]
	s_waitcnt lgkmcnt(14)
	v_perm_b32 v105, v111, v105, s59
	v_perm_b32 v104, v110, v104, s59
	v_perm_b32 v103, v109, v108, s59
	v_perm_b32 v102, v107, v106, s59
	ds_read_b128 v[106:109], v158 offset:2304
	s_ashr_i32 s25, s24, 31
	s_waitcnt lgkmcnt(1)
	v_mfma_f32_16x16x32_bf16 v[110:113], v[98:101], v[102:105], 0
	v_perm_b32 v117, v125, v117, s59
	v_perm_b32 v116, v124, v116, s59
	v_perm_b32 v115, v123, v115, s59
	v_perm_b32 v114, v122, v114, s59
	s_add_u32 s2, s46, s28
	v_ashrrev_i32_e32 v97, 31, v96
	v_mfma_f32_16x16x32_bf16 v[98:101], v[98:101], v[114:117], 0
	s_addc_u32 s3, s47, s29
	v_cvt_pk_bf16_f32 v110, v110, v111
	v_cvt_pk_bf16_f32 v111, v112, v113
	v_lshl_add_u64 v[112:113], s[2:3], 0, v[120:121]
	v_lshlrev_b32_e32 v120, 1, v119
	v_mov_b32_e32 v121, v131
	v_lshl_add_u64 v[96:97], v[96:97], 1, s[82:83]
	s_lshl_b64 s[2:3], s[24:25], 14
	v_lshl_add_u64 v[136:137], v[112:113], 0, v[120:121]
	v_lshl_add_u64 v[138:139], v[96:97], 0, v[130:131]
	v_lshl_or_b32 v142, v119, 8, s2
	v_mov_b32_e32 v143, s3
	global_store_dwordx2 v[136:137], v[110:111], off
	v_cvt_pk_bf16_f32 v96, -v98, s0
	v_lshl_add_u64 v[110:111], v[138:139], 0, v[142:143]
	global_store_short v[110:111], v96, off
	v_cvt_pk_bf16_f32 v96, -v99, s0
	global_store_short v[110:111], v96, off offset:256
	s_waitcnt lgkmcnt(0)
	v_mfma_f32_16x16x32_bf16 v[96:99], v[106:109], v[102:105], 0
	v_cvt_pk_bf16_f32 v100, -v100, s0
	global_store_short v[110:111], v100, off offset:512
	v_cvt_pk_bf16_f32 v100, -v101, s0
	v_mfma_f32_16x16x32_bf16 v[106:109], v[106:109], v[114:117], 0
	global_store_short v[110:111], v100, off offset:768
	s_nop 2
	v_cvt_pk_bf16_f32 v96, v96, v97
	v_cvt_pk_bf16_f32 v97, v98, v99
	global_store_dwordx2 v[136:137], v[96:97], off offset:32
	v_or_b32_e32 v96, 0x1000, v142
	v_mov_b32_e32 v97, s3
	v_cvt_pk_bf16_f32 v98, -v106, s0
	v_lshl_add_u64 v[96:97], v[138:139], 0, v[96:97]
	global_store_short v[96:97], v98, off
	v_or_b32_e32 v96, 0x1100, v142
	v_mov_b32_e32 v97, s3
	v_cvt_pk_bf16_f32 v98, -v107, s0
	v_lshl_add_u64 v[96:97], v[138:139], 0, v[96:97]
	global_store_short v[96:97], v98, off
	ds_read_b128 v[96:99], v158 offset:4608
	v_or_b32_e32 v100, 0x1200, v142
	v_mov_b32_e32 v101, s3
	v_cvt_pk_bf16_f32 v106, -v108, s0
	v_lshl_add_u64 v[100:101], v[138:139], 0, v[100:101]
	global_store_short v[100:101], v106, off
	v_cvt_pk_bf16_f32 v119, -v109, s0
	ds_read_b128 v[106:109], v158 offset:4672
	s_waitcnt lgkmcnt(1)
	v_mfma_f32_16x16x32_bf16 v[110:113], v[96:99], v[102:105], 0
	v_perm_b32 v123, v148, v147, s59
	v_perm_b32 v122, v146, v134, s59
	v_perm_b32 v121, v133, v128, s59
	v_mfma_f32_16x16x32_bf16 v[96:99], v[96:99], v[114:117], 0
	v_perm_b32 v120, v127, v126, s59
	v_perm_b32 v127, v157, v155, s59
	v_perm_b32 v126, v154, v153, s59
	v_perm_b32 v125, v152, v151, s59
	v_perm_b32 v124, v150, v149, s59
	s_waitcnt lgkmcnt(0)
	v_mfma_f32_16x16x32_bf16 v[110:113], v[106:109], v[120:123], v[110:113]
	v_or_b32_e32 v100, 0x1300, v142
	v_mov_b32_e32 v101, s3
	v_lshl_add_u64 v[100:101], v[138:139], 0, v[100:101]
	v_mfma_f32_16x16x32_bf16 v[96:99], v[106:109], v[124:127], v[96:99]
	ds_read_b128 v[106:109], v158 offset:6912
	global_store_short v[100:101], v119, off
	s_nop 1
	v_cvt_pk_bf16_f32 v100, v110, v111
	v_cvt_pk_bf16_f32 v101, v112, v113
	ds_read_b128 v[110:113], v158 offset:6976
	global_store_dwordx2 v[136:137], v[100:101], off offset:64
	v_or_b32_e32 v100, 0x2000, v142
	v_mov_b32_e32 v101, s3
	v_cvt_pk_bf16_f32 v96, -v96, s0
	v_lshl_add_u64 v[100:101], v[138:139], 0, v[100:101]
	global_store_short v[100:101], v96, off
	v_cvt_pk_bf16_f32 v100, -v97, s0
	v_or_b32_e32 v96, 0x2100, v142
	v_mov_b32_e32 v97, s3
	v_lshl_add_u64 v[96:97], v[138:139], 0, v[96:97]
	global_store_short v[96:97], v100, off
	s_waitcnt lgkmcnt(1)
	v_mfma_f32_16x16x32_bf16 v[100:103], v[106:109], v[102:105], 0
	v_or_b32_e32 v96, 0x2200, v142
	v_mov_b32_e32 v97, s3
	v_cvt_pk_bf16_f32 v98, -v98, s0
	v_mfma_f32_16x16x32_bf16 v[104:107], v[106:109], v[114:117], 0
	v_lshl_add_u64 v[96:97], v[138:139], 0, v[96:97]
	global_store_short v[96:97], v98, off
	v_cvt_pk_bf16_f32 v114, -v99, s0
	v_or_b32_e32 v108, 0x2300, v142
	s_waitcnt lgkmcnt(0)
	v_mfma_f32_16x16x32_bf16 v[96:99], v[110:113], v[120:123], v[100:103]
	v_mov_b32_e32 v109, s3
	v_and_b32_e32 v116, 48, v118
	s_add_u32 s2, s44, s28
	v_lshl_add_u64 v[100:101], v[138:139], 0, v[108:109]
	global_store_short v[100:101], v114, off
	v_mfma_f32_16x16x32_bf16 v[100:103], v[110:113], v[124:127], v[104:107]
	s_nop 1
	v_cvt_pk_bf16_f32 v96, v96, v97
	v_cvt_pk_bf16_f32 v97, v98, v99
	global_store_dwordx2 v[136:137], v[96:97], off offset:96
	v_or_b32_e32 v96, 0x3000, v142
	v_mov_b32_e32 v97, s3
	s_nop 0
	v_cvt_pk_bf16_f32 v98, -v100, s0
	v_lshl_add_u64 v[96:97], v[138:139], 0, v[96:97]
	global_store_short v[96:97], v98, off
	v_or_b32_e32 v96, 0x3100, v142
	v_mov_b32_e32 v97, s3
	v_cvt_pk_bf16_f32 v98, -v101, s0
	v_lshl_add_u64 v[96:97], v[138:139], 0, v[96:97]
	global_store_short v[96:97], v98, off
	v_or_b32_e32 v96, 0x3200, v142
	v_mov_b32_e32 v97, s3
	v_cvt_pk_bf16_f32 v98, -v102, s0
	v_lshl_add_u64 v[96:97], v[138:139], 0, v[96:97]
	v_or_b32_e32 v142, 0x3300, v142
	global_store_short v[96:97], v98, off
	v_cvt_pk_bf16_f32 v98, -v103, s0
	v_lshl_add_u64 v[96:97], v[138:139], 0, v[142:143]
	global_store_short v[96:97], v98, off
	v_lshl_add_u32 v96, v116, 2, 0
	v_add_u32_e32 v108, 0x1f700, v96
	ds_read_b128 v[96:99], v108
	v_ashrrev_i32_e32 v112, 2, v132
	v_lshlrev_b32_e32 v100, 1, v112
	v_mul_u32_u24_e32 v101, 0x110, v116
	v_add3_u32 v113, 0, v100, v101
	s_waitcnt lgkmcnt(0)
	v_sub_f32_e32 v96, v141, v96
	v_sub_f32_e32 v97, v141, v97
	v_mul_f32_e32 v96, 0x3fb8aa3b, v96
	v_mul_f32_e32 v97, 0x3fb8aa3b, v97
	v_exp_f32_e32 v96, v96
	v_exp_f32_e32 v97, v97
	ds_read_b128 v[100:103], v108 offset:16
	ds_read_b128 v[104:107], v108 offset:32
	ds_read_b128 v[108:111], v108 offset:48
	ds_read_u16 v114, v113 offset:17408
	ds_read_u16 v115, v113 offset:17680
	ds_read_u16 v117, v113 offset:17952
	ds_read_u16 v118, v113 offset:18224
	ds_read_u16 v119, v113 offset:18496
	ds_read_u16 v120, v113 offset:18768
	ds_read_u16 v121, v113 offset:19040
	ds_read_u16 v122, v113 offset:19312
	s_waitcnt lgkmcnt(6)
	v_lshlrev_b32_e32 v115, 16, v115
	v_lshlrev_b32_e32 v114, 16, v114
	v_pk_mul_f32 v[96:97], v[96:97], v[114:115]
	v_sub_f32_e32 v98, v141, v98
	v_sub_f32_e32 v99, v141, v99
	v_cvt_pk_bf16_f32 v96, v96, v97
	v_sub_f32_e32 v97, v141, v100
	v_mul_f32_e32 v98, 0x3fb8aa3b, v98
	v_mul_f32_e32 v99, 0x3fb8aa3b, v99
	v_mul_f32_e32 v97, 0x3fb8aa3b, v97
	v_exp_f32_e32 v98, v98
	v_exp_f32_e32 v99, v99
	v_exp_f32_e32 v100, v97
	v_sub_f32_e32 v97, v141, v101
	v_mul_f32_e32 v97, 0x3fb8aa3b, v97
	v_exp_f32_e32 v101, v97
	s_waitcnt lgkmcnt(4)
	v_lshlrev_b32_e32 v115, 16, v118
	v_lshlrev_b32_e32 v114, 16, v117
	v_pk_mul_f32 v[98:99], v[98:99], v[114:115]
	s_addc_u32 s3, s45, s29
	v_cvt_pk_bf16_f32 v97, v98, v99
	s_waitcnt lgkmcnt(2)
	v_lshlrev_b32_e32 v99, 16, v120
	v_lshlrev_b32_e32 v98, 16, v119
	v_pk_mul_f32 v[98:99], v[100:101], v[98:99]
	v_sub_f32_e32 v100, v141, v102
	v_sub_f32_e32 v101, v141, v103
	v_mul_f32_e32 v100, 0x3fb8aa3b, v100
	v_mul_f32_e32 v101, 0x3fb8aa3b, v101
	v_exp_f32_e32 v100, v100
	v_exp_f32_e32 v101, v101
	s_waitcnt lgkmcnt(0)
	v_lshlrev_b32_e32 v103, 16, v122
	v_lshlrev_b32_e32 v102, 16, v121
	v_cvt_pk_bf16_f32 v98, v98, v99
	v_pk_mul_f32 v[100:101], v[100:101], v[102:103]
	v_lshlrev_b32_e32 v130, 1, v116
	v_cvt_pk_bf16_f32 v99, v100, v101
	v_sub_f32_e32 v100, v141, v104
	v_sub_f32_e32 v101, v141, v105
	v_mul_f32_e32 v100, 0x3fb8aa3b, v100
	v_mul_f32_e32 v101, 0x3fb8aa3b, v101
	v_exp_f32_e32 v100, v100
	v_exp_f32_e32 v101, v101
	ds_read_u16 v102, v113 offset:19584
	ds_read_u16 v103, v113 offset:19856
	ds_read_u16 v104, v113 offset:20128
	ds_read_u16 v105, v113 offset:20400
	ds_read_u16 v114, v113 offset:20672
	ds_read_u16 v115, v113 offset:20944
	ds_read_u16 v117, v113 offset:21216
	ds_read_u16 v113, v113 offset:21488
	s_waitcnt lgkmcnt(6)
	v_lshlrev_b32_e32 v103, 16, v103
	v_lshlrev_b32_e32 v102, 16, v102
	v_pk_mul_f32 v[100:101], v[100:101], v[102:103]
	v_sub_f32_e32 v102, v141, v106
	v_sub_f32_e32 v103, v141, v107
	v_mul_f32_e32 v102, 0x3fb8aa3b, v102
	v_mul_f32_e32 v103, 0x3fb8aa3b, v103
	v_exp_f32_e32 v102, v102
	v_exp_f32_e32 v103, v103
	v_cvt_pk_bf16_f32 v100, v100, v101
	v_sub_f32_e32 v101, v141, v108
	s_waitcnt lgkmcnt(4)
	v_lshlrev_b32_e32 v105, 16, v105
	v_lshlrev_b32_e32 v104, 16, v104
	v_mul_f32_e32 v101, 0x3fb8aa3b, v101
	v_pk_mul_f32 v[102:103], v[102:103], v[104:105]
	v_exp_f32_e32 v104, v101
	v_sub_f32_e32 v101, v141, v109
	v_mul_f32_e32 v101, 0x3fb8aa3b, v101
	v_exp_f32_e32 v105, v101
	v_cvt_pk_bf16_f32 v101, v102, v103
	s_waitcnt lgkmcnt(2)
	v_lshlrev_b32_e32 v103, 16, v115
	v_lshlrev_b32_e32 v102, 16, v114
	v_pk_mul_f32 v[102:103], v[104:105], v[102:103]
	v_sub_f32_e32 v104, v141, v110
	v_sub_f32_e32 v105, v141, v111
	v_mul_f32_e32 v104, 0x3fb8aa3b, v104
	v_mul_f32_e32 v105, 0x3fb8aa3b, v105
	v_exp_f32_e32 v104, v104
	v_exp_f32_e32 v105, v105
	s_waitcnt lgkmcnt(0)
	v_lshlrev_b32_e32 v107, 16, v113
	v_lshlrev_b32_e32 v106, 16, v117
	v_ashrrev_i32_e32 v113, 31, v112
	v_pk_mul_f32 v[104:105], v[104:105], v[106:107]
	v_cvt_pk_bf16_f32 v102, v102, v103
	v_cvt_pk_bf16_f32 v103, v104, v105
	v_lshlrev_b64 v[104:105], 7, v[112:113]
	v_lshl_add_u64 v[104:105], s[2:3], 0, v[104:105]
	v_lshl_add_u64 v[104:105], v[104:105], 0, v[130:131]
	v_cmp_eq_u32_e32 vcc, 0, v132
	global_store_dwordx4 v[104:105], v[96:99], off
	global_store_dwordx4 v[104:105], v[100:103], off offset:16
	s_and_saveexec_b64 s[2:3], vcc
	s_cbranch_execz .LBB0_358
	v_mul_f32_e32 v96, 0x3fb8aa3b, v141
	v_exp_f32_e32 v96, v96
	s_lshl_b64 s[4:5], s[24:25], 2
	s_add_u32 s4, s80, s4
	s_addc_u32 s5, s81, s5
	global_store_dword v131, v96, s[4:5]
	s_branch .LBB0_358
